# grid barrier: non-leader workgroups poll the top-level generation word directly instead of the per-XCD generation word (one hop less); plus rstd reuse
# speedup vs baseline: 1.0049x; 1.0020x over previous
.LBB0_284:
	v_readlane_b32 s4, v252, 16
	v_readlane_b32 s5, v252, 17
	v_mov_b32_e32 v0, 1
	v_sub_u32_e32 v5, 0, v3
	s_nop 2
	global_atomic_add v4, v1, v0, s[4:5] sc0
	v_cvt_f32_u32_e32 v0, v3
	v_rcp_iflag_f32_e32 v0, v0
	s_nop 0
	v_mul_f32_e32 v0, 0x4f7ffffe, v0
	v_cvt_u32_f32_e32 v0, v0
	v_mul_lo_u32 v5, v5, v0
	v_mul_hi_u32 v5, v0, v5
	v_add_u32_e32 v0, v0, v5
	s_waitcnt vmcnt(0)
	v_mul_hi_u32 v0, v4, v0
	v_mul_lo_u32 v5, v0, v3
	v_sub_u32_e32 v5, v4, v5
	v_add_u32_e32 v6, 1, v0
	v_cmp_ge_u32_e32 vcc, v5, v3
	v_add_u32_e32 v4, 1, v4
	s_nop 0
	v_cndmask_b32_e32 v0, v0, v6, vcc
	v_sub_u32_e32 v6, v5, v3
	v_cndmask_b32_e32 v5, v5, v6, vcc
	v_add_u32_e32 v6, 1, v0
	v_cmp_ge_u32_e32 vcc, v5, v3
	s_nop 1
	v_cndmask_b32_e32 v0, v0, v6, vcc
	v_mul_lo_u32 v5, v3, v0
	v_add_u32_e32 v3, v5, v3
	v_cmp_ne_u32_e32 vcc, v4, v3
	s_and_saveexec_b64 s[4:5], vcc
	s_xor_b64 s[4:5], exec, s[4:5]
	s_cbranch_execz .LBB0_298
	v_readlane_b32 s6, v252, 22
	v_readlane_b32 s7, v252, 23
	s_waitcnt lgkmcnt(0)
	s_nop 3
	global_load_dword v2, v1, s[6:7] sc1
	s_waitcnt vmcnt(0)
	v_cmp_eq_u32_e32 vcc, v2, v0
	s_and_saveexec_b64 s[6:7], vcc
	s_cbranch_execz .LBB0_297
	s_mov_b32 s18, 1
	s_mov_b64 s[8:9], 0
	s_branch .LBB0_288

.LBB0_363:
	v_readlane_b32 s6, v252, 16
	v_readlane_b32 s7, v252, 17
	v_mov_b32_e32 v0, 1
	v_sub_u32_e32 v5, 0, v3
	s_nop 2
	global_atomic_add v4, v1, v0, s[6:7] sc0
	v_cvt_f32_u32_e32 v0, v3
	v_rcp_iflag_f32_e32 v0, v0
	s_nop 0
	v_mul_f32_e32 v0, 0x4f7ffffe, v0
	v_cvt_u32_f32_e32 v0, v0
	v_mul_lo_u32 v5, v5, v0
	v_mul_hi_u32 v5, v0, v5
	v_add_u32_e32 v0, v0, v5
	s_waitcnt vmcnt(0)
	v_mul_hi_u32 v0, v4, v0
	v_mul_lo_u32 v5, v0, v3
	v_sub_u32_e32 v5, v4, v5
	v_add_u32_e32 v6, 1, v0
	v_cmp_ge_u32_e32 vcc, v5, v3
	v_add_u32_e32 v4, 1, v4
	s_nop 0
	v_cndmask_b32_e32 v0, v0, v6, vcc
	v_sub_u32_e32 v6, v5, v3
	v_cndmask_b32_e32 v5, v5, v6, vcc
	v_add_u32_e32 v6, 1, v0
	v_cmp_ge_u32_e32 vcc, v5, v3
	s_nop 1
	v_cndmask_b32_e32 v0, v0, v6, vcc
	v_mul_lo_u32 v5, v3, v0
	v_add_u32_e32 v3, v5, v3
	v_cmp_ne_u32_e32 vcc, v4, v3
	s_and_saveexec_b64 s[6:7], vcc
	s_xor_b64 s[6:7], exec, s[6:7]
	s_cbranch_execz .LBB0_377
	v_readlane_b32 s8, v252, 22
	v_readlane_b32 s9, v252, 23
	s_waitcnt lgkmcnt(0)
	s_nop 3
	global_load_dword v2, v1, s[8:9] sc1
	s_waitcnt vmcnt(0)
	v_cmp_eq_u32_e32 vcc, v2, v0
	s_and_saveexec_b64 s[8:9], vcc
	s_cbranch_execz .LBB0_376
	s_mov_b32 s18, 1
	s_mov_b64 s[10:11], 0
	s_branch .LBB0_367
